# v19 + mid-block s_setprio 0/1 toggle pairs deleted in the four GEMM K-loops (32 MFMAs issue uninterrupted)
# speedup vs baseline: 1.0038x; 1.0038x over previous
.LBB0_32:
	s_add_u32 s28, s54, 0xfff80080
	s_addc_u32 s29, s55, -1
	s_add_i32 s30, 0, 0x10000
	s_cmp_eq_u32 s27, 28
	s_cselect_b32 s79, s13, s29
	s_cselect_b32 s78, s16, s28
	s_cselect_b32 s69, s9, s26
	s_cselect_b32 s68, s24, s25
	s_add_i32 s31, 0, 0x14000
	v_add_u32_e32 v142, s30, v184
	v_add_u32_e32 v172, s31, v184
	ds_read_b128 v[130:133], v142
	ds_read_b128 v[134:137], v142 offset:1024
	ds_read_b128 v[138:141], v142 offset:2048
	ds_read_b128 v[142:145], v142 offset:3072
	ds_read_b128 v[146:149], v172
	ds_read_b128 v[150:153], v172 offset:1024
	ds_read_b128 v[154:157], v172 offset:2048
	ds_read_b128 v[172:175], v172 offset:3072
	v_lshl_add_u64 v[212:213], s[54:55], 0, v[166:167]
	s_add_i32 m0, s42, 0xc000
	ds_read_b128 v[176:179], v186
	ds_read_b128 v[180:183], v186 offset:1024
	ds_read_b128 v[188:191], v186 offset:2048
	ds_read_b128 v[192:195], v186 offset:3072
	ds_read_b128 v[196:199], v186 offset:4096
	ds_read_b128 v[200:203], v186 offset:5120
	ds_read_b128 v[204:207], v186 offset:6144
	ds_read_b128 v[208:211], v186 offset:7168
	global_load_lds_dwordx4 v[212:213], off
	v_lshl_add_u64 v[212:213], s[54:55], 0, v[168:169]
	s_add_i32 m0, s42, 0xe000
	s_nop 0
	global_load_lds_dwordx4 v[212:213], off
	s_waitcnt vmcnt(8)
	s_waitcnt lgkmcnt(0)
	s_barrier
	s_setprio 1
	s_waitcnt lgkmcnt(0)
	v_mfma_f32_16x16x32_bf16 v[126:129], v[130:133], v[176:179], v[126:129]
	v_mfma_f32_16x16x32_bf16 v[126:129], v[134:137], v[180:183], v[126:129]
	v_mfma_f32_16x16x32_bf16 v[122:125], v[142:145], v[180:183], v[122:125]
	v_mfma_f32_16x16x32_bf16 v[122:125], v[138:141], v[176:179], v[122:125]
	v_mfma_f32_16x16x32_bf16 v[118:121], v[146:149], v[176:179], v[118:121]
	v_mfma_f32_16x16x32_bf16 v[118:121], v[150:153], v[180:183], v[118:121]
	v_mfma_f32_16x16x32_bf16 v[114:117], v[172:175], v[180:183], v[114:117]
	v_mfma_f32_16x16x32_bf16 v[114:117], v[154:157], v[176:179], v[114:117]
	v_mfma_f32_16x16x32_bf16 v[98:101], v[154:157], v[188:191], v[98:101]
	v_mfma_f32_16x16x32_bf16 v[98:101], v[172:175], v[192:195], v[98:101]
	v_mfma_f32_16x16x32_bf16 v[102:105], v[150:153], v[192:195], v[102:105]
	v_mfma_f32_16x16x32_bf16 v[102:105], v[146:149], v[188:191], v[102:105]
	v_mfma_f32_16x16x32_bf16 v[106:109], v[138:141], v[188:191], v[106:109]
	v_mfma_f32_16x16x32_bf16 v[106:109], v[142:145], v[192:195], v[106:109]
	v_mfma_f32_16x16x32_bf16 v[110:113], v[134:137], v[192:195], v[110:113]
	v_mfma_f32_16x16x32_bf16 v[110:113], v[130:133], v[188:191], v[110:113]
	v_mfma_f32_16x16x32_bf16 v[94:97], v[130:133], v[196:199], v[94:97]
	v_mfma_f32_16x16x32_bf16 v[94:97], v[134:137], v[200:203], v[94:97]
	v_mfma_f32_16x16x32_bf16 v[90:93], v[142:145], v[200:203], v[90:93]
	v_mfma_f32_16x16x32_bf16 v[90:93], v[138:141], v[196:199], v[90:93]
	v_mfma_f32_16x16x32_bf16 v[86:89], v[146:149], v[196:199], v[86:89]
	v_mfma_f32_16x16x32_bf16 v[86:89], v[150:153], v[200:203], v[86:89]
	v_mfma_f32_16x16x32_bf16 v[82:85], v[172:175], v[200:203], v[82:85]
	v_mfma_f32_16x16x32_bf16 v[82:85], v[154:157], v[196:199], v[82:85]
	v_mfma_f32_16x16x32_bf16 v[66:69], v[154:157], v[204:207], v[66:69]
	v_mfma_f32_16x16x32_bf16 v[66:69], v[172:175], v[208:211], v[66:69]
	v_mfma_f32_16x16x32_bf16 v[70:73], v[150:153], v[208:211], v[70:73]
	v_mfma_f32_16x16x32_bf16 v[70:73], v[146:149], v[204:207], v[70:73]
	v_mfma_f32_16x16x32_bf16 v[74:77], v[138:141], v[204:207], v[74:77]
	v_mfma_f32_16x16x32_bf16 v[74:77], v[142:145], v[208:211], v[74:77]
	v_mfma_f32_16x16x32_bf16 v[78:81], v[134:137], v[208:211], v[78:81]
	v_mfma_f32_16x16x32_bf16 v[78:81], v[130:133], v[204:207], v[78:81]
	s_setprio 0
	s_barrier
	s_add_i32 s28, s30, s11
	v_lshl_add_u64 v[212:213], s[68:69], 0, v[160:161]
	s_mov_b32 m0, s28
	ds_read_b128 v[176:179], v186 offset:16384
	ds_read_b128 v[180:183], v186 offset:17408
	ds_read_b128 v[188:191], v186 offset:18432
	ds_read_b128 v[192:195], v186 offset:19456
	ds_read_b128 v[196:199], v186 offset:20480
	ds_read_b128 v[200:203], v186 offset:21504
	ds_read_b128 v[204:207], v186 offset:22528
	ds_read_b128 v[208:211], v186 offset:23552
	global_load_lds_dwordx4 v[212:213], off
	s_add_i32 m0, s28, 0x2000
	s_add_u32 s28, s68, 0x80000
	v_lshl_add_u64 v[232:233], s[68:69], 0, v[164:165]
	s_addc_u32 s29, s69, 0
	s_add_i32 s30, s31, s11
	global_load_lds_dwordx4 v[232:233], off
	v_lshl_add_u64 v[234:235], s[28:29], 0, v[160:161]
	s_mov_b32 m0, s30
	v_lshl_add_u64 v[236:237], s[78:79], 0, v[162:163]
	global_load_lds_dwordx4 v[234:235], off
	v_lshl_add_u64 v[234:235], s[28:29], 0, v[164:165]
	s_add_i32 m0, s30, 0x2000
	s_nop 0
	global_load_lds_dwordx4 v[234:235], off
	v_lshl_add_u64 v[234:235], s[78:79], 0, v[158:159]
	s_mov_b32 m0, s42
	s_nop 0
	global_load_lds_dwordx4 v[234:235], off
	s_mov_b32 m0, s57
	s_nop 0
	global_load_lds_dwordx4 v[236:237], off
	s_waitcnt vmcnt(8)
	s_waitcnt lgkmcnt(0)
	s_barrier
	s_setprio 1
	s_waitcnt lgkmcnt(0)
	v_mfma_f32_16x16x32_bf16 v[62:65], v[130:133], v[176:179], v[62:65]
	v_mfma_f32_16x16x32_bf16 v[62:65], v[134:137], v[180:183], v[62:65]
	v_mfma_f32_16x16x32_bf16 v[58:61], v[142:145], v[180:183], v[58:61]
	v_mfma_f32_16x16x32_bf16 v[58:61], v[138:141], v[176:179], v[58:61]
	v_mfma_f32_16x16x32_bf16 v[54:57], v[146:149], v[176:179], v[54:57]
	v_mfma_f32_16x16x32_bf16 v[54:57], v[150:153], v[180:183], v[54:57]
	v_mfma_f32_16x16x32_bf16 v[50:53], v[172:175], v[180:183], v[50:53]
	v_mfma_f32_16x16x32_bf16 v[50:53], v[154:157], v[176:179], v[50:53]
	v_mfma_f32_16x16x32_bf16 v[34:37], v[154:157], v[188:191], v[34:37]
	v_mfma_f32_16x16x32_bf16 v[34:37], v[172:175], v[192:195], v[34:37]
	v_mfma_f32_16x16x32_bf16 v[38:41], v[150:153], v[192:195], v[38:41]
	v_mfma_f32_16x16x32_bf16 v[38:41], v[146:149], v[188:191], v[38:41]
	v_mfma_f32_16x16x32_bf16 v[42:45], v[138:141], v[188:191], v[42:45]
	v_mfma_f32_16x16x32_bf16 v[42:45], v[142:145], v[192:195], v[42:45]
	v_mfma_f32_16x16x32_bf16 v[46:49], v[134:137], v[192:195], v[46:49]
	v_mfma_f32_16x16x32_bf16 v[46:49], v[130:133], v[188:191], v[46:49]
	v_mfma_f32_16x16x32_bf16 v[30:33], v[130:133], v[196:199], v[30:33]
	v_mfma_f32_16x16x32_bf16 v[30:33], v[134:137], v[200:203], v[30:33]
	v_mfma_f32_16x16x32_bf16 v[26:29], v[142:145], v[200:203], v[26:29]
	v_mfma_f32_16x16x32_bf16 v[26:29], v[138:141], v[196:199], v[26:29]
	v_mfma_f32_16x16x32_bf16 v[22:25], v[146:149], v[196:199], v[22:25]
	v_mfma_f32_16x16x32_bf16 v[22:25], v[150:153], v[200:203], v[22:25]
	v_mfma_f32_16x16x32_bf16 v[18:21], v[172:175], v[200:203], v[18:21]
	v_mfma_f32_16x16x32_bf16 v[18:21], v[154:157], v[196:199], v[18:21]
	v_mfma_f32_16x16x32_bf16 v[2:5], v[154:157], v[204:207], v[2:5]
	v_mfma_f32_16x16x32_bf16 v[2:5], v[172:175], v[208:211], v[2:5]
	v_mfma_f32_16x16x32_bf16 v[6:9], v[150:153], v[208:211], v[6:9]
	v_mfma_f32_16x16x32_bf16 v[6:9], v[146:149], v[204:207], v[6:9]
	v_mfma_f32_16x16x32_bf16 v[10:13], v[138:141], v[204:207], v[10:13]
	v_mfma_f32_16x16x32_bf16 v[10:13], v[142:145], v[208:211], v[10:13]
	v_mfma_f32_16x16x32_bf16 v[14:17], v[134:137], v[208:211], v[14:17]
	v_mfma_f32_16x16x32_bf16 v[14:17], v[130:133], v[204:207], v[14:17]
	s_setprio 0
	s_barrier
	s_add_i32 s30, 0, 0x18000
	s_add_i32 s31, 0, 0x1c000
	v_add_u32_e32 v142, s30, v184
	v_add_u32_e32 v172, s31, v184
	ds_read_b128 v[130:133], v142
	ds_read_b128 v[134:137], v142 offset:1024
	ds_read_b128 v[138:141], v142 offset:2048
	ds_read_b128 v[142:145], v142 offset:3072
	ds_read_b128 v[146:149], v172
	ds_read_b128 v[150:153], v172 offset:1024
	ds_read_b128 v[154:157], v172 offset:2048
	ds_read_b128 v[172:175], v172 offset:3072
	s_add_u32 s28, s78, 0x80000
	s_addc_u32 s29, s79, 0
	s_mov_b32 m0, s67
	v_lshl_add_u64 v[238:239], s[28:29], 0, v[158:159]
	ds_read_b128 v[176:179], v186 offset:32768
	ds_read_b128 v[180:183], v186 offset:33792
	ds_read_b128 v[188:191], v186 offset:34816
	ds_read_b128 v[192:195], v186 offset:35840
	ds_read_b128 v[196:199], v186 offset:36864
	ds_read_b128 v[200:203], v186 offset:37888
	ds_read_b128 v[204:207], v186 offset:38912
	ds_read_b128 v[208:211], v186 offset:39936
	global_load_lds_dwordx4 v[238:239], off
	v_lshl_add_u64 v[238:239], s[28:29], 0, v[162:163]
	s_mov_b32 m0, s72
	s_nop 0
	global_load_lds_dwordx4 v[238:239], off
	s_waitcnt vmcnt(8)
	s_waitcnt lgkmcnt(0)
	s_barrier
	s_setprio 1
	s_waitcnt lgkmcnt(0)
	v_mfma_f32_16x16x32_bf16 v[126:129], v[130:133], v[176:179], v[126:129]
	v_mfma_f32_16x16x32_bf16 v[126:129], v[134:137], v[180:183], v[126:129]
	v_mfma_f32_16x16x32_bf16 v[122:125], v[142:145], v[180:183], v[122:125]
	v_mfma_f32_16x16x32_bf16 v[122:125], v[138:141], v[176:179], v[122:125]
	v_mfma_f32_16x16x32_bf16 v[118:121], v[146:149], v[176:179], v[118:121]
	v_mfma_f32_16x16x32_bf16 v[118:121], v[150:153], v[180:183], v[118:121]
	v_mfma_f32_16x16x32_bf16 v[114:117], v[172:175], v[180:183], v[114:117]
	v_mfma_f32_16x16x32_bf16 v[114:117], v[154:157], v[176:179], v[114:117]
	v_mfma_f32_16x16x32_bf16 v[98:101], v[154:157], v[188:191], v[98:101]
	v_mfma_f32_16x16x32_bf16 v[98:101], v[172:175], v[192:195], v[98:101]
	v_mfma_f32_16x16x32_bf16 v[102:105], v[150:153], v[192:195], v[102:105]
	v_mfma_f32_16x16x32_bf16 v[102:105], v[146:149], v[188:191], v[102:105]
	v_mfma_f32_16x16x32_bf16 v[106:109], v[138:141], v[188:191], v[106:109]
	v_mfma_f32_16x16x32_bf16 v[106:109], v[142:145], v[192:195], v[106:109]
	v_mfma_f32_16x16x32_bf16 v[110:113], v[134:137], v[192:195], v[110:113]
	v_mfma_f32_16x16x32_bf16 v[110:113], v[130:133], v[188:191], v[110:113]
	v_mfma_f32_16x16x32_bf16 v[94:97], v[130:133], v[196:199], v[94:97]
	v_mfma_f32_16x16x32_bf16 v[94:97], v[134:137], v[200:203], v[94:97]
	v_mfma_f32_16x16x32_bf16 v[90:93], v[142:145], v[200:203], v[90:93]
	v_mfma_f32_16x16x32_bf16 v[90:93], v[138:141], v[196:199], v[90:93]
	v_mfma_f32_16x16x32_bf16 v[86:89], v[146:149], v[196:199], v[86:89]
	v_mfma_f32_16x16x32_bf16 v[86:89], v[150:153], v[200:203], v[86:89]
	v_mfma_f32_16x16x32_bf16 v[82:85], v[172:175], v[200:203], v[82:85]
	v_mfma_f32_16x16x32_bf16 v[82:85], v[154:157], v[196:199], v[82:85]
	v_mfma_f32_16x16x32_bf16 v[66:69], v[154:157], v[204:207], v[66:69]
	v_mfma_f32_16x16x32_bf16 v[66:69], v[172:175], v[208:211], v[66:69]
	v_mfma_f32_16x16x32_bf16 v[70:73], v[150:153], v[208:211], v[70:73]
	v_mfma_f32_16x16x32_bf16 v[70:73], v[146:149], v[204:207], v[70:73]
	v_mfma_f32_16x16x32_bf16 v[74:77], v[138:141], v[204:207], v[74:77]
	v_mfma_f32_16x16x32_bf16 v[74:77], v[142:145], v[208:211], v[74:77]
	v_mfma_f32_16x16x32_bf16 v[78:81], v[134:137], v[208:211], v[78:81]
	v_mfma_f32_16x16x32_bf16 v[78:81], v[130:133], v[204:207], v[78:81]
	s_setprio 0
	s_barrier
	s_add_i32 s28, s30, s11
	v_lshl_add_u64 v[212:213], v[212:213], 0, s[62:63]
	s_mov_b32 m0, s28
	ds_read_b128 v[176:179], v186 offset:49152
	ds_read_b128 v[180:183], v186 offset:50176
	ds_read_b128 v[188:191], v186 offset:51200
	ds_read_b128 v[192:195], v186 offset:52224
	ds_read_b128 v[196:199], v186 offset:53248
	ds_read_b128 v[200:203], v186 offset:54272
	ds_read_b128 v[204:207], v186 offset:55296
	ds_read_b128 v[208:211], v186 offset:56320
	global_load_lds_dwordx4 v[212:213], off
	s_add_i32 m0, s28, 0x2000
	s_add_u32 s28, s68, 0x80080
	v_lshl_add_u64 v[212:213], v[232:233], 0, s[62:63]
	s_addc_u32 s29, s69, 0
	s_add_i32 s30, s31, s11
	global_load_lds_dwordx4 v[212:213], off
	v_lshl_add_u64 v[212:213], s[28:29], 0, v[160:161]
	s_mov_b32 m0, s30
	s_nop 0
	global_load_lds_dwordx4 v[212:213], off
	v_lshl_add_u64 v[212:213], s[28:29], 0, v[164:165]
	s_add_i32 m0, s30, 0x2000
	s_nop 0
	global_load_lds_dwordx4 v[212:213], off
	v_lshl_add_u64 v[212:213], v[234:235], 0, s[62:63]
	s_mov_b32 m0, s18
	s_nop 0
	global_load_lds_dwordx4 v[212:213], off
	v_lshl_add_u64 v[212:213], v[236:237], 0, s[62:63]
	s_mov_b32 m0, s19
	s_nop 0
	global_load_lds_dwordx4 v[212:213], off
	s_waitcnt vmcnt(8)
	s_waitcnt lgkmcnt(0)
	s_barrier
	s_setprio 1
	s_waitcnt lgkmcnt(0)
	v_mfma_f32_16x16x32_bf16 v[62:65], v[130:133], v[176:179], v[62:65]
	v_mfma_f32_16x16x32_bf16 v[62:65], v[134:137], v[180:183], v[62:65]
	v_mfma_f32_16x16x32_bf16 v[58:61], v[142:145], v[180:183], v[58:61]
	v_mfma_f32_16x16x32_bf16 v[58:61], v[138:141], v[176:179], v[58:61]
	v_mfma_f32_16x16x32_bf16 v[54:57], v[146:149], v[176:179], v[54:57]
	v_mfma_f32_16x16x32_bf16 v[54:57], v[150:153], v[180:183], v[54:57]
	v_mfma_f32_16x16x32_bf16 v[50:53], v[172:175], v[180:183], v[50:53]
	v_mfma_f32_16x16x32_bf16 v[50:53], v[154:157], v[176:179], v[50:53]
	v_mfma_f32_16x16x32_bf16 v[34:37], v[154:157], v[188:191], v[34:37]
	v_mfma_f32_16x16x32_bf16 v[34:37], v[172:175], v[192:195], v[34:37]
	v_mfma_f32_16x16x32_bf16 v[38:41], v[150:153], v[192:195], v[38:41]
	v_mfma_f32_16x16x32_bf16 v[38:41], v[146:149], v[188:191], v[38:41]
	v_mfma_f32_16x16x32_bf16 v[42:45], v[138:141], v[188:191], v[42:45]
	v_mfma_f32_16x16x32_bf16 v[42:45], v[142:145], v[192:195], v[42:45]
	v_mfma_f32_16x16x32_bf16 v[46:49], v[134:137], v[192:195], v[46:49]
	v_mfma_f32_16x16x32_bf16 v[46:49], v[130:133], v[188:191], v[46:49]
	v_mfma_f32_16x16x32_bf16 v[30:33], v[130:133], v[196:199], v[30:33]
	v_mfma_f32_16x16x32_bf16 v[30:33], v[134:137], v[200:203], v[30:33]
	v_mfma_f32_16x16x32_bf16 v[26:29], v[142:145], v[200:203], v[26:29]
	v_mfma_f32_16x16x32_bf16 v[26:29], v[138:141], v[196:199], v[26:29]
	v_mfma_f32_16x16x32_bf16 v[22:25], v[146:149], v[196:199], v[22:25]
	v_mfma_f32_16x16x32_bf16 v[22:25], v[150:153], v[200:203], v[22:25]
	v_mfma_f32_16x16x32_bf16 v[18:21], v[172:175], v[200:203], v[18:21]
	v_mfma_f32_16x16x32_bf16 v[18:21], v[154:157], v[196:199], v[18:21]
	v_mfma_f32_16x16x32_bf16 v[2:5], v[154:157], v[204:207], v[2:5]
	v_mfma_f32_16x16x32_bf16 v[2:5], v[172:175], v[208:211], v[2:5]
	v_mfma_f32_16x16x32_bf16 v[6:9], v[150:153], v[208:211], v[6:9]
	v_mfma_f32_16x16x32_bf16 v[6:9], v[146:149], v[204:207], v[6:9]
	v_mfma_f32_16x16x32_bf16 v[10:13], v[138:141], v[204:207], v[10:13]
	v_mfma_f32_16x16x32_bf16 v[10:13], v[142:145], v[208:211], v[10:13]
	v_mfma_f32_16x16x32_bf16 v[14:17], v[134:137], v[208:211], v[14:17]
	v_mfma_f32_16x16x32_bf16 v[14:17], v[130:133], v[204:207], v[14:17]
	s_setprio 0
	s_barrier
	s_add_i32 s27, s27, 2
	s_add_u32 s54, s54, 0x100
	s_addc_u32 s55, s55, 0
	s_add_u32 s25, s25, 0x100
	s_addc_u32 s26, s26, 0
	s_cmp_gt_u32 s27, 29
	s_cbranch_scc0 .LBB0_32
	s_and_b64 vcc, exec, s[2:3]
	s_cbranch_vccz .LBB0_35
	s_barrier

.LBB0_132:
	s_add_u32 s23, s48, 0xfff80080
	s_addc_u32 s24, s49, -1
	s_add_i32 s25, 0, 0x10000
	s_cmp_eq_u32 s22, 28
	s_cselect_b32 s69, s3, s24
	s_cselect_b32 s68, s18, s23
	s_cselect_b32 s51, s1, s21
	s_cselect_b32 s50, s19, s20
	s_add_i32 s23, 0, 0x14000
	v_add_u32_e32 v156, s25, v165
	v_add_u32_e32 v169, s23, v165
	ds_read_b128 v[144:147], v156
	ds_read_b128 v[148:151], v156 offset:1024
	ds_read_b128 v[152:155], v156 offset:2048
	ds_read_b128 v[156:159], v156 offset:3072
	ds_read_b128 v[160:163], v169
	ds_read_b128 v[170:173], v169 offset:1024
	ds_read_b128 v[174:177], v169 offset:2048
	ds_read_b128 v[178:181], v169 offset:3072
	v_lshl_add_u64 v[232:233], s[48:49], 0, v[140:141]
	s_add_i32 m0, s45, 0xc000
	ds_read_b128 v[182:185], v168
	ds_read_b128 v[186:189], v168 offset:1024
	ds_read_b128 v[190:193], v168 offset:2048
	ds_read_b128 v[194:197], v168 offset:3072
	ds_read_b128 v[198:201], v168 offset:4096
	ds_read_b128 v[202:205], v168 offset:5120
	ds_read_b128 v[206:209], v168 offset:6144
	ds_read_b128 v[210:213], v168 offset:7168
	global_load_lds_dwordx4 v[232:233], off
	v_lshl_add_u64 v[232:233], s[48:49], 0, v[142:143]
	s_add_i32 m0, s45, 0xe000
	s_nop 0
	global_load_lds_dwordx4 v[232:233], off
	s_waitcnt vmcnt(8)
	s_waitcnt lgkmcnt(0)
	s_barrier
	s_setprio 1
	s_waitcnt lgkmcnt(0)
	v_mfma_f32_16x16x32_bf16 v[126:129], v[144:147], v[182:185], v[126:129]
	v_mfma_f32_16x16x32_bf16 v[126:129], v[148:151], v[186:189], v[126:129]
	v_mfma_f32_16x16x32_bf16 v[122:125], v[156:159], v[186:189], v[122:125]
	v_mfma_f32_16x16x32_bf16 v[122:125], v[152:155], v[182:185], v[122:125]
	v_mfma_f32_16x16x32_bf16 v[118:121], v[160:163], v[182:185], v[118:121]
	v_mfma_f32_16x16x32_bf16 v[118:121], v[170:173], v[186:189], v[118:121]
	v_mfma_f32_16x16x32_bf16 v[114:117], v[178:181], v[186:189], v[114:117]
	v_mfma_f32_16x16x32_bf16 v[114:117], v[174:177], v[182:185], v[114:117]
	v_mfma_f32_16x16x32_bf16 v[90:93], v[174:177], v[190:193], v[90:93]
	v_mfma_f32_16x16x32_bf16 v[90:93], v[178:181], v[194:197], v[90:93]
	v_mfma_f32_16x16x32_bf16 v[98:101], v[170:173], v[194:197], v[98:101]
	v_mfma_f32_16x16x32_bf16 v[98:101], v[160:163], v[190:193], v[98:101]
	v_mfma_f32_16x16x32_bf16 v[106:109], v[152:155], v[190:193], v[106:109]
	v_mfma_f32_16x16x32_bf16 v[106:109], v[156:159], v[194:197], v[106:109]
	v_mfma_f32_16x16x32_bf16 v[110:113], v[148:151], v[194:197], v[110:113]
	v_mfma_f32_16x16x32_bf16 v[110:113], v[144:147], v[190:193], v[110:113]
	v_mfma_f32_16x16x32_bf16 v[102:105], v[144:147], v[198:201], v[102:105]
	v_mfma_f32_16x16x32_bf16 v[102:105], v[148:151], v[202:205], v[102:105]
	v_mfma_f32_16x16x32_bf16 v[94:97], v[156:159], v[202:205], v[94:97]
	v_mfma_f32_16x16x32_bf16 v[94:97], v[152:155], v[198:201], v[94:97]
	v_mfma_f32_16x16x32_bf16 v[82:85], v[160:163], v[198:201], v[82:85]
	v_mfma_f32_16x16x32_bf16 v[82:85], v[170:173], v[202:205], v[82:85]
	v_mfma_f32_16x16x32_bf16 v[74:77], v[178:181], v[202:205], v[74:77]
	v_mfma_f32_16x16x32_bf16 v[74:77], v[174:177], v[198:201], v[74:77]
	v_mfma_f32_16x16x32_bf16 v[66:69], v[174:177], v[206:209], v[66:69]
	v_mfma_f32_16x16x32_bf16 v[66:69], v[178:181], v[210:213], v[66:69]
	v_mfma_f32_16x16x32_bf16 v[70:73], v[170:173], v[210:213], v[70:73]
	v_mfma_f32_16x16x32_bf16 v[70:73], v[160:163], v[206:209], v[70:73]
	v_mfma_f32_16x16x32_bf16 v[78:81], v[152:155], v[206:209], v[78:81]
	v_mfma_f32_16x16x32_bf16 v[78:81], v[156:159], v[210:213], v[78:81]
	v_mfma_f32_16x16x32_bf16 v[86:89], v[148:151], v[210:213], v[86:89]
	v_mfma_f32_16x16x32_bf16 v[86:89], v[144:147], v[206:209], v[86:89]
	s_setprio 0
	s_barrier
	s_add_i32 s24, s25, s16
	v_lshl_add_u64 v[232:233], s[50:51], 0, v[132:133]
	s_mov_b32 m0, s24
	ds_read_b128 v[182:185], v168 offset:16384
	ds_read_b128 v[186:189], v168 offset:17408
	ds_read_b128 v[190:193], v168 offset:18432
	ds_read_b128 v[194:197], v168 offset:19456
	ds_read_b128 v[198:201], v168 offset:20480
	ds_read_b128 v[202:205], v168 offset:21504
	ds_read_b128 v[206:209], v168 offset:22528
	ds_read_b128 v[210:213], v168 offset:23552
	global_load_lds_dwordx4 v[232:233], off
	s_add_i32 m0, s24, 0x2000
	s_add_u32 s24, s50, 0x80000
	v_lshl_add_u64 v[234:235], s[50:51], 0, v[136:137]
	s_addc_u32 s25, s51, 0
	s_add_i32 s23, s23, s16
	global_load_lds_dwordx4 v[234:235], off
	v_lshl_add_u64 v[236:237], s[24:25], 0, v[132:133]
	s_mov_b32 m0, s23
	v_lshl_add_u64 v[238:239], s[68:69], 0, v[134:135]
	global_load_lds_dwordx4 v[236:237], off
	v_lshl_add_u64 v[236:237], s[24:25], 0, v[136:137]
	s_add_i32 m0, s23, 0x2000
	s_nop 0
	global_load_lds_dwordx4 v[236:237], off
	v_lshl_add_u64 v[236:237], s[68:69], 0, v[130:131]
	s_mov_b32 m0, s45
	s_nop 0
	global_load_lds_dwordx4 v[236:237], off
	s_mov_b32 m0, s57
	s_nop 0
	global_load_lds_dwordx4 v[238:239], off
	s_waitcnt vmcnt(8)
	s_waitcnt lgkmcnt(0)
	s_barrier
	s_setprio 1
	s_waitcnt lgkmcnt(0)
	v_mfma_f32_16x16x32_bf16 v[62:65], v[144:147], v[182:185], v[62:65]
	v_mfma_f32_16x16x32_bf16 v[62:65], v[148:151], v[186:189], v[62:65]
	v_mfma_f32_16x16x32_bf16 v[58:61], v[156:159], v[186:189], v[58:61]
	v_mfma_f32_16x16x32_bf16 v[58:61], v[152:155], v[182:185], v[58:61]
	v_mfma_f32_16x16x32_bf16 v[50:53], v[160:163], v[182:185], v[50:53]
	v_mfma_f32_16x16x32_bf16 v[50:53], v[170:173], v[186:189], v[50:53]
	v_mfma_f32_16x16x32_bf16 v[42:45], v[178:181], v[186:189], v[42:45]
	v_mfma_f32_16x16x32_bf16 v[42:45], v[174:177], v[182:185], v[42:45]
	v_mfma_f32_16x16x32_bf16 v[26:29], v[174:177], v[190:193], v[26:29]
	v_mfma_f32_16x16x32_bf16 v[26:29], v[178:181], v[194:197], v[26:29]
	v_mfma_f32_16x16x32_bf16 v[34:37], v[170:173], v[194:197], v[34:37]
	v_mfma_f32_16x16x32_bf16 v[34:37], v[160:163], v[190:193], v[34:37]
	v_mfma_f32_16x16x32_bf16 v[46:49], v[152:155], v[190:193], v[46:49]
	v_mfma_f32_16x16x32_bf16 v[46:49], v[156:159], v[194:197], v[46:49]
	v_mfma_f32_16x16x32_bf16 v[54:57], v[148:151], v[194:197], v[54:57]
	v_mfma_f32_16x16x32_bf16 v[54:57], v[144:147], v[190:193], v[54:57]
	v_mfma_f32_16x16x32_bf16 v[38:41], v[144:147], v[198:201], v[38:41]
	v_mfma_f32_16x16x32_bf16 v[38:41], v[148:151], v[202:205], v[38:41]
	v_mfma_f32_16x16x32_bf16 v[30:33], v[156:159], v[202:205], v[30:33]
	v_mfma_f32_16x16x32_bf16 v[30:33], v[152:155], v[198:201], v[30:33]
	v_mfma_f32_16x16x32_bf16 v[18:21], v[160:163], v[198:201], v[18:21]
	v_mfma_f32_16x16x32_bf16 v[18:21], v[170:173], v[202:205], v[18:21]
	v_mfma_f32_16x16x32_bf16 v[10:13], v[178:181], v[202:205], v[10:13]
	v_mfma_f32_16x16x32_bf16 v[10:13], v[174:177], v[198:201], v[10:13]
	v_mfma_f32_16x16x32_bf16 v[2:5], v[174:177], v[206:209], v[2:5]
	v_mfma_f32_16x16x32_bf16 v[2:5], v[178:181], v[210:213], v[2:5]
	v_mfma_f32_16x16x32_bf16 v[6:9], v[170:173], v[210:213], v[6:9]
	v_mfma_f32_16x16x32_bf16 v[6:9], v[160:163], v[206:209], v[6:9]
	v_mfma_f32_16x16x32_bf16 v[14:17], v[152:155], v[206:209], v[14:17]
	v_mfma_f32_16x16x32_bf16 v[14:17], v[156:159], v[210:213], v[14:17]
	v_mfma_f32_16x16x32_bf16 v[22:25], v[148:151], v[210:213], v[22:25]
	v_mfma_f32_16x16x32_bf16 v[22:25], v[144:147], v[206:209], v[22:25]
	s_setprio 0
	s_barrier
	s_add_i32 s23, 0, 0x18000
	s_add_i32 s26, 0, 0x1c000
	v_add_u32_e32 v156, s23, v165
	v_add_u32_e32 v169, s26, v165
	ds_read_b128 v[144:147], v156
	ds_read_b128 v[148:151], v156 offset:1024
	ds_read_b128 v[152:155], v156 offset:2048
	ds_read_b128 v[156:159], v156 offset:3072
	ds_read_b128 v[160:163], v169
	ds_read_b128 v[170:173], v169 offset:1024
	ds_read_b128 v[174:177], v169 offset:2048
	ds_read_b128 v[178:181], v169 offset:3072
	s_add_u32 s24, s68, 0x80000
	s_addc_u32 s25, s69, 0
	s_mov_b32 m0, s42
	v_lshl_add_u64 v[240:241], s[24:25], 0, v[130:131]
	ds_read_b128 v[182:185], v168 offset:32768
	ds_read_b128 v[186:189], v168 offset:33792
	ds_read_b128 v[190:193], v168 offset:34816
	ds_read_b128 v[194:197], v168 offset:35840
	ds_read_b128 v[198:201], v168 offset:36864
	ds_read_b128 v[202:205], v168 offset:37888
	ds_read_b128 v[206:209], v168 offset:38912
	ds_read_b128 v[210:213], v168 offset:39936
	global_load_lds_dwordx4 v[240:241], off
	v_lshl_add_u64 v[240:241], s[24:25], 0, v[134:135]
	s_mov_b32 m0, s6
	s_nop 0
	global_load_lds_dwordx4 v[240:241], off
	s_waitcnt vmcnt(8)
	s_waitcnt lgkmcnt(0)
	s_barrier
	s_setprio 1
	s_waitcnt lgkmcnt(0)
	v_mfma_f32_16x16x32_bf16 v[126:129], v[144:147], v[182:185], v[126:129]
	v_mfma_f32_16x16x32_bf16 v[126:129], v[148:151], v[186:189], v[126:129]
	v_mfma_f32_16x16x32_bf16 v[122:125], v[156:159], v[186:189], v[122:125]
	v_mfma_f32_16x16x32_bf16 v[122:125], v[152:155], v[182:185], v[122:125]
	v_mfma_f32_16x16x32_bf16 v[118:121], v[160:163], v[182:185], v[118:121]
	v_mfma_f32_16x16x32_bf16 v[118:121], v[170:173], v[186:189], v[118:121]
	v_mfma_f32_16x16x32_bf16 v[114:117], v[178:181], v[186:189], v[114:117]
	v_mfma_f32_16x16x32_bf16 v[114:117], v[174:177], v[182:185], v[114:117]
	v_mfma_f32_16x16x32_bf16 v[90:93], v[174:177], v[190:193], v[90:93]
	v_mfma_f32_16x16x32_bf16 v[90:93], v[178:181], v[194:197], v[90:93]
	v_mfma_f32_16x16x32_bf16 v[98:101], v[170:173], v[194:197], v[98:101]
	v_mfma_f32_16x16x32_bf16 v[98:101], v[160:163], v[190:193], v[98:101]
	v_mfma_f32_16x16x32_bf16 v[106:109], v[152:155], v[190:193], v[106:109]
	v_mfma_f32_16x16x32_bf16 v[106:109], v[156:159], v[194:197], v[106:109]
	v_mfma_f32_16x16x32_bf16 v[110:113], v[148:151], v[194:197], v[110:113]
	v_mfma_f32_16x16x32_bf16 v[110:113], v[144:147], v[190:193], v[110:113]
	v_mfma_f32_16x16x32_bf16 v[102:105], v[144:147], v[198:201], v[102:105]
	v_mfma_f32_16x16x32_bf16 v[102:105], v[148:151], v[202:205], v[102:105]
	v_mfma_f32_16x16x32_bf16 v[94:97], v[156:159], v[202:205], v[94:97]
	v_mfma_f32_16x16x32_bf16 v[94:97], v[152:155], v[198:201], v[94:97]
	v_mfma_f32_16x16x32_bf16 v[82:85], v[160:163], v[198:201], v[82:85]
	v_mfma_f32_16x16x32_bf16 v[82:85], v[170:173], v[202:205], v[82:85]
	v_mfma_f32_16x16x32_bf16 v[74:77], v[178:181], v[202:205], v[74:77]
	v_mfma_f32_16x16x32_bf16 v[74:77], v[174:177], v[198:201], v[74:77]
	v_mfma_f32_16x16x32_bf16 v[66:69], v[174:177], v[206:209], v[66:69]
	v_mfma_f32_16x16x32_bf16 v[66:69], v[178:181], v[210:213], v[66:69]
	v_mfma_f32_16x16x32_bf16 v[70:73], v[170:173], v[210:213], v[70:73]
	v_mfma_f32_16x16x32_bf16 v[70:73], v[160:163], v[206:209], v[70:73]
	v_mfma_f32_16x16x32_bf16 v[78:81], v[152:155], v[206:209], v[78:81]
	v_mfma_f32_16x16x32_bf16 v[78:81], v[156:159], v[210:213], v[78:81]
	v_mfma_f32_16x16x32_bf16 v[86:89], v[148:151], v[210:213], v[86:89]
	v_mfma_f32_16x16x32_bf16 v[86:89], v[144:147], v[206:209], v[86:89]
	s_setprio 0
	s_barrier
	s_add_i32 s23, s23, s16
	v_lshl_add_u64 v[232:233], v[232:233], 0, s[62:63]
	s_mov_b32 m0, s23
	ds_read_b128 v[182:185], v168 offset:49152
	ds_read_b128 v[186:189], v168 offset:50176
	ds_read_b128 v[190:193], v168 offset:51200
	ds_read_b128 v[194:197], v168 offset:52224
	ds_read_b128 v[198:201], v168 offset:53248
	ds_read_b128 v[202:205], v168 offset:54272
	ds_read_b128 v[206:209], v168 offset:55296
	ds_read_b128 v[210:213], v168 offset:56320
	global_load_lds_dwordx4 v[232:233], off
	s_add_i32 m0, s23, 0x2000
	s_add_u32 s24, s50, 0x80080
	v_lshl_add_u64 v[232:233], v[234:235], 0, s[62:63]
	s_addc_u32 s25, s51, 0
	s_add_i32 s23, s26, s16
	global_load_lds_dwordx4 v[232:233], off
	v_lshl_add_u64 v[232:233], s[24:25], 0, v[132:133]
	s_mov_b32 m0, s23
	s_nop 0
	global_load_lds_dwordx4 v[232:233], off
	v_lshl_add_u64 v[232:233], s[24:25], 0, v[136:137]
	s_add_i32 m0, s23, 0x2000
	s_nop 0
	global_load_lds_dwordx4 v[232:233], off
	v_lshl_add_u64 v[232:233], v[236:237], 0, s[62:63]
	s_mov_b32 m0, s76
	s_nop 0
	global_load_lds_dwordx4 v[232:233], off
	v_lshl_add_u64 v[232:233], v[238:239], 0, s[62:63]
	s_mov_b32 m0, s77
	s_nop 0
	global_load_lds_dwordx4 v[232:233], off
	s_waitcnt vmcnt(8)
	s_waitcnt lgkmcnt(0)
	s_barrier
	s_setprio 1
	s_waitcnt lgkmcnt(0)
	v_mfma_f32_16x16x32_bf16 v[62:65], v[144:147], v[182:185], v[62:65]
	v_mfma_f32_16x16x32_bf16 v[62:65], v[148:151], v[186:189], v[62:65]
	v_mfma_f32_16x16x32_bf16 v[58:61], v[156:159], v[186:189], v[58:61]
	v_mfma_f32_16x16x32_bf16 v[58:61], v[152:155], v[182:185], v[58:61]
	v_mfma_f32_16x16x32_bf16 v[50:53], v[160:163], v[182:185], v[50:53]
	v_mfma_f32_16x16x32_bf16 v[50:53], v[170:173], v[186:189], v[50:53]
	v_mfma_f32_16x16x32_bf16 v[42:45], v[178:181], v[186:189], v[42:45]
	v_mfma_f32_16x16x32_bf16 v[42:45], v[174:177], v[182:185], v[42:45]
	v_mfma_f32_16x16x32_bf16 v[26:29], v[174:177], v[190:193], v[26:29]
	v_mfma_f32_16x16x32_bf16 v[26:29], v[178:181], v[194:197], v[26:29]
	v_mfma_f32_16x16x32_bf16 v[34:37], v[170:173], v[194:197], v[34:37]
	v_mfma_f32_16x16x32_bf16 v[34:37], v[160:163], v[190:193], v[34:37]
	v_mfma_f32_16x16x32_bf16 v[46:49], v[152:155], v[190:193], v[46:49]
	v_mfma_f32_16x16x32_bf16 v[46:49], v[156:159], v[194:197], v[46:49]
	v_mfma_f32_16x16x32_bf16 v[54:57], v[148:151], v[194:197], v[54:57]
	v_mfma_f32_16x16x32_bf16 v[54:57], v[144:147], v[190:193], v[54:57]
	v_mfma_f32_16x16x32_bf16 v[38:41], v[144:147], v[198:201], v[38:41]
	v_mfma_f32_16x16x32_bf16 v[38:41], v[148:151], v[202:205], v[38:41]
	v_mfma_f32_16x16x32_bf16 v[30:33], v[156:159], v[202:205], v[30:33]
	v_mfma_f32_16x16x32_bf16 v[30:33], v[152:155], v[198:201], v[30:33]
	v_mfma_f32_16x16x32_bf16 v[18:21], v[160:163], v[198:201], v[18:21]
	v_mfma_f32_16x16x32_bf16 v[18:21], v[170:173], v[202:205], v[18:21]
	v_mfma_f32_16x16x32_bf16 v[10:13], v[178:181], v[202:205], v[10:13]
	v_mfma_f32_16x16x32_bf16 v[10:13], v[174:177], v[198:201], v[10:13]
	v_mfma_f32_16x16x32_bf16 v[2:5], v[174:177], v[206:209], v[2:5]
	v_mfma_f32_16x16x32_bf16 v[2:5], v[178:181], v[210:213], v[2:5]
	v_mfma_f32_16x16x32_bf16 v[6:9], v[170:173], v[210:213], v[6:9]
	v_mfma_f32_16x16x32_bf16 v[6:9], v[160:163], v[206:209], v[6:9]
	v_mfma_f32_16x16x32_bf16 v[14:17], v[152:155], v[206:209], v[14:17]
	v_mfma_f32_16x16x32_bf16 v[14:17], v[156:159], v[210:213], v[14:17]
	v_mfma_f32_16x16x32_bf16 v[22:25], v[148:151], v[210:213], v[22:25]
	v_mfma_f32_16x16x32_bf16 v[22:25], v[144:147], v[206:209], v[22:25]
	s_setprio 0
	s_barrier
	s_add_i32 s22, s22, 2
	s_add_u32 s48, s48, 0x100
	s_addc_u32 s49, s49, 0
	s_add_u32 s20, s20, 0x100
	s_addc_u32 s21, s21, 0
	s_cmp_gt_u32 s22, 29
	s_cbranch_scc0 .LBB0_132
	s_and_b64 vcc, exec, s[10:11]
	s_cbranch_vccz .LBB0_135
	s_barrier

.LBB0_238:
	s_add_u32 s10, s12, 0x100
	s_addc_u32 s11, s13, 0
	s_add_i32 s23, 0, 0x10000
	s_cmpk_eq_i32 s22, 0x52
	s_cselect_b32 vcc_hi, s47, s11
	s_cselect_b32 vcc_lo, s46, s10
	s_cselect_b32 s51, s49, s21
	s_cselect_b32 s50, s48, s20
	s_add_i32 s24, 0, 0x14000
	v_add_u32_e32 v142, s23, v194
	v_add_u32_e32 v158, s24, v194
	ds_read_b128 v[122:125], v142
	ds_read_b128 v[126:129], v142 offset:1024
	ds_read_b128 v[138:141], v142 offset:2048
	ds_read_b128 v[142:145], v142 offset:3072
	ds_read_b128 v[146:149], v158
	ds_read_b128 v[150:153], v158 offset:1024
	ds_read_b128 v[154:157], v158 offset:2048
	ds_read_b128 v[158:161], v158 offset:3072
	v_lshl_add_u64 v[212:213], s[12:13], 0, v[170:171]
	s_add_i32 m0, s57, 0xc000
	ds_read_b128 v[174:177], v198
	ds_read_b128 v[178:181], v198 offset:1024
	ds_read_b128 v[182:185], v198 offset:2048
	ds_read_b128 v[186:189], v198 offset:3072
	ds_read_b128 v[190:193], v198 offset:4096
	ds_read_b128 v[200:203], v198 offset:5120
	ds_read_b128 v[204:207], v198 offset:6144
	ds_read_b128 v[208:211], v198 offset:7168
	global_load_lds_dwordx4 v[212:213], off
	v_lshl_add_u64 v[212:213], s[12:13], 0, v[172:173]
	s_add_i32 m0, s57, 0xe000
	s_nop 0
	global_load_lds_dwordx4 v[212:213], off
	s_waitcnt vmcnt(8)
	s_waitcnt lgkmcnt(0)
	s_barrier
	s_setprio 1
	s_waitcnt lgkmcnt(0)
	v_mfma_f32_16x16x32_bf16 v[134:137], v[122:125], v[174:177], v[134:137]
	v_mfma_f32_16x16x32_bf16 v[134:137], v[126:129], v[178:181], v[134:137]
	v_mfma_f32_16x16x32_bf16 v[130:133], v[142:145], v[178:181], v[130:133]
	v_mfma_f32_16x16x32_bf16 v[130:133], v[138:141], v[174:177], v[130:133]
	v_mfma_f32_16x16x32_bf16 v[118:121], v[146:149], v[174:177], v[118:121]
	v_mfma_f32_16x16x32_bf16 v[118:121], v[150:153], v[178:181], v[118:121]
	v_mfma_f32_16x16x32_bf16 v[114:117], v[158:161], v[178:181], v[114:117]
	v_mfma_f32_16x16x32_bf16 v[114:117], v[154:157], v[174:177], v[114:117]
	v_mfma_f32_16x16x32_bf16 v[98:101], v[154:157], v[182:185], v[98:101]
	v_mfma_f32_16x16x32_bf16 v[98:101], v[158:161], v[186:189], v[98:101]
	v_mfma_f32_16x16x32_bf16 v[102:105], v[150:153], v[186:189], v[102:105]
	v_mfma_f32_16x16x32_bf16 v[102:105], v[146:149], v[182:185], v[102:105]
	v_mfma_f32_16x16x32_bf16 v[106:109], v[138:141], v[182:185], v[106:109]
	v_mfma_f32_16x16x32_bf16 v[106:109], v[142:145], v[186:189], v[106:109]
	v_mfma_f32_16x16x32_bf16 v[110:113], v[126:129], v[186:189], v[110:113]
	v_mfma_f32_16x16x32_bf16 v[110:113], v[122:125], v[182:185], v[110:113]
	v_mfma_f32_16x16x32_bf16 v[94:97], v[122:125], v[190:193], v[94:97]
	v_mfma_f32_16x16x32_bf16 v[94:97], v[126:129], v[200:203], v[94:97]
	v_mfma_f32_16x16x32_bf16 v[90:93], v[142:145], v[200:203], v[90:93]
	v_mfma_f32_16x16x32_bf16 v[90:93], v[138:141], v[190:193], v[90:93]
	v_mfma_f32_16x16x32_bf16 v[86:89], v[146:149], v[190:193], v[86:89]
	v_mfma_f32_16x16x32_bf16 v[86:89], v[150:153], v[200:203], v[86:89]
	v_mfma_f32_16x16x32_bf16 v[82:85], v[158:161], v[200:203], v[82:85]
	v_mfma_f32_16x16x32_bf16 v[82:85], v[154:157], v[190:193], v[82:85]
	v_mfma_f32_16x16x32_bf16 v[66:69], v[154:157], v[204:207], v[66:69]
	v_mfma_f32_16x16x32_bf16 v[66:69], v[158:161], v[208:211], v[66:69]
	v_mfma_f32_16x16x32_bf16 v[70:73], v[150:153], v[208:211], v[70:73]
	v_mfma_f32_16x16x32_bf16 v[70:73], v[146:149], v[204:207], v[70:73]
	v_mfma_f32_16x16x32_bf16 v[74:77], v[138:141], v[204:207], v[74:77]
	v_mfma_f32_16x16x32_bf16 v[74:77], v[142:145], v[208:211], v[74:77]
	v_mfma_f32_16x16x32_bf16 v[78:81], v[126:129], v[208:211], v[78:81]
	v_mfma_f32_16x16x32_bf16 v[78:81], v[122:125], v[204:207], v[78:81]
	s_setprio 0
	s_barrier
	s_add_i32 s12, s23, s42
	v_lshl_add_u64 v[212:213], s[50:51], 0, v[164:165]
	s_mov_b32 m0, s12
	ds_read_b128 v[174:177], v198 offset:16384
	ds_read_b128 v[178:181], v198 offset:17408
	ds_read_b128 v[182:185], v198 offset:18432
	ds_read_b128 v[186:189], v198 offset:19456
	ds_read_b128 v[190:193], v198 offset:20480
	ds_read_b128 v[200:203], v198 offset:21504
	ds_read_b128 v[204:207], v198 offset:22528
	ds_read_b128 v[208:211], v198 offset:23552
	global_load_lds_dwordx4 v[212:213], off
	s_add_i32 m0, s12, 0x2000
	s_add_u32 s12, s50, 0x158000
	v_lshl_add_u64 v[232:233], s[50:51], 0, v[168:169]
	s_addc_u32 s13, s51, 0
	s_add_i32 s23, s24, s42
	global_load_lds_dwordx4 v[232:233], off
	v_lshl_add_u64 v[234:235], s[12:13], 0, v[164:165]
	s_mov_b32 m0, s23
	v_lshl_add_u64 v[236:237], vcc, 0, v[166:167]
	global_load_lds_dwordx4 v[234:235], off
	v_lshl_add_u64 v[234:235], s[12:13], 0, v[168:169]
	s_add_i32 m0, s23, 0x2000
	s_nop 0
	global_load_lds_dwordx4 v[234:235], off
	v_lshl_add_u64 v[234:235], vcc, 0, v[162:163]
	s_mov_b32 m0, s57
	s_nop 0
	global_load_lds_dwordx4 v[234:235], off
	s_mov_b32 m0, s58
	s_nop 0
	global_load_lds_dwordx4 v[236:237], off
	s_waitcnt vmcnt(8)
	s_waitcnt lgkmcnt(0)
	s_barrier
	s_setprio 1
	s_waitcnt lgkmcnt(0)
	v_mfma_f32_16x16x32_bf16 v[62:65], v[122:125], v[174:177], v[62:65]
	v_mfma_f32_16x16x32_bf16 v[62:65], v[126:129], v[178:181], v[62:65]
	v_mfma_f32_16x16x32_bf16 v[58:61], v[142:145], v[178:181], v[58:61]
	v_mfma_f32_16x16x32_bf16 v[58:61], v[138:141], v[174:177], v[58:61]
	v_mfma_f32_16x16x32_bf16 v[54:57], v[146:149], v[174:177], v[54:57]
	v_mfma_f32_16x16x32_bf16 v[54:57], v[150:153], v[178:181], v[54:57]
	v_mfma_f32_16x16x32_bf16 v[50:53], v[158:161], v[178:181], v[50:53]
	v_mfma_f32_16x16x32_bf16 v[50:53], v[154:157], v[174:177], v[50:53]
	v_mfma_f32_16x16x32_bf16 v[34:37], v[154:157], v[182:185], v[34:37]
	v_mfma_f32_16x16x32_bf16 v[34:37], v[158:161], v[186:189], v[34:37]
	v_mfma_f32_16x16x32_bf16 v[38:41], v[150:153], v[186:189], v[38:41]
	v_mfma_f32_16x16x32_bf16 v[38:41], v[146:149], v[182:185], v[38:41]
	v_mfma_f32_16x16x32_bf16 v[42:45], v[138:141], v[182:185], v[42:45]
	v_mfma_f32_16x16x32_bf16 v[42:45], v[142:145], v[186:189], v[42:45]
	v_mfma_f32_16x16x32_bf16 v[46:49], v[126:129], v[186:189], v[46:49]
	v_mfma_f32_16x16x32_bf16 v[46:49], v[122:125], v[182:185], v[46:49]
	v_mfma_f32_16x16x32_bf16 v[30:33], v[122:125], v[190:193], v[30:33]
	v_mfma_f32_16x16x32_bf16 v[30:33], v[126:129], v[200:203], v[30:33]
	v_mfma_f32_16x16x32_bf16 v[26:29], v[142:145], v[200:203], v[26:29]
	v_mfma_f32_16x16x32_bf16 v[26:29], v[138:141], v[190:193], v[26:29]
	v_mfma_f32_16x16x32_bf16 v[22:25], v[146:149], v[190:193], v[22:25]
	v_mfma_f32_16x16x32_bf16 v[22:25], v[150:153], v[200:203], v[22:25]
	v_mfma_f32_16x16x32_bf16 v[18:21], v[158:161], v[200:203], v[18:21]
	v_mfma_f32_16x16x32_bf16 v[18:21], v[154:157], v[190:193], v[18:21]
	v_mfma_f32_16x16x32_bf16 v[2:5], v[154:157], v[204:207], v[2:5]
	v_mfma_f32_16x16x32_bf16 v[2:5], v[158:161], v[208:211], v[2:5]
	v_mfma_f32_16x16x32_bf16 v[6:9], v[150:153], v[208:211], v[6:9]
	v_mfma_f32_16x16x32_bf16 v[6:9], v[146:149], v[204:207], v[6:9]
	v_mfma_f32_16x16x32_bf16 v[10:13], v[138:141], v[204:207], v[10:13]
	v_mfma_f32_16x16x32_bf16 v[10:13], v[142:145], v[208:211], v[10:13]
	v_mfma_f32_16x16x32_bf16 v[14:17], v[126:129], v[208:211], v[14:17]
	v_mfma_f32_16x16x32_bf16 v[14:17], v[122:125], v[204:207], v[14:17]
	s_setprio 0
	s_barrier
	s_add_i32 s23, 0, 0x18000
	s_add_i32 s24, 0, 0x1c000
	v_add_u32_e32 v142, s23, v194
	v_add_u32_e32 v158, s24, v194
	ds_read_b128 v[122:125], v142
	ds_read_b128 v[126:129], v142 offset:1024
	ds_read_b128 v[138:141], v142 offset:2048
	ds_read_b128 v[142:145], v142 offset:3072
	ds_read_b128 v[146:149], v158
	ds_read_b128 v[150:153], v158 offset:1024
	ds_read_b128 v[154:157], v158 offset:2048
	ds_read_b128 v[158:161], v158 offset:3072
	s_add_u32 s12, vcc_lo, 0x158000
	s_addc_u32 s13, vcc_hi, 0
	s_mov_b32 m0, s67
	v_lshl_add_u64 v[238:239], s[12:13], 0, v[162:163]
	ds_read_b128 v[174:177], v198 offset:32768
	ds_read_b128 v[178:181], v198 offset:33792
	ds_read_b128 v[182:185], v198 offset:34816
	ds_read_b128 v[186:189], v198 offset:35840
	ds_read_b128 v[190:193], v198 offset:36864
	ds_read_b128 v[200:203], v198 offset:37888
	ds_read_b128 v[204:207], v198 offset:38912
	ds_read_b128 v[208:211], v198 offset:39936
	global_load_lds_dwordx4 v[238:239], off
	v_lshl_add_u64 v[238:239], s[12:13], 0, v[166:167]
	s_mov_b32 m0, s76
	s_nop 0
	global_load_lds_dwordx4 v[238:239], off
	s_waitcnt vmcnt(8)
	s_waitcnt lgkmcnt(0)
	s_barrier
	s_setprio 1
	s_waitcnt lgkmcnt(0)
	v_mfma_f32_16x16x32_bf16 v[134:137], v[122:125], v[174:177], v[134:137]
	v_mfma_f32_16x16x32_bf16 v[134:137], v[126:129], v[178:181], v[134:137]
	v_mfma_f32_16x16x32_bf16 v[130:133], v[142:145], v[178:181], v[130:133]
	v_mfma_f32_16x16x32_bf16 v[130:133], v[138:141], v[174:177], v[130:133]
	v_mfma_f32_16x16x32_bf16 v[118:121], v[146:149], v[174:177], v[118:121]
	v_mfma_f32_16x16x32_bf16 v[118:121], v[150:153], v[178:181], v[118:121]
	v_mfma_f32_16x16x32_bf16 v[114:117], v[158:161], v[178:181], v[114:117]
	v_mfma_f32_16x16x32_bf16 v[114:117], v[154:157], v[174:177], v[114:117]
	v_mfma_f32_16x16x32_bf16 v[98:101], v[154:157], v[182:185], v[98:101]
	v_mfma_f32_16x16x32_bf16 v[98:101], v[158:161], v[186:189], v[98:101]
	v_mfma_f32_16x16x32_bf16 v[102:105], v[150:153], v[186:189], v[102:105]
	v_mfma_f32_16x16x32_bf16 v[102:105], v[146:149], v[182:185], v[102:105]
	v_mfma_f32_16x16x32_bf16 v[106:109], v[138:141], v[182:185], v[106:109]
	v_mfma_f32_16x16x32_bf16 v[106:109], v[142:145], v[186:189], v[106:109]
	v_mfma_f32_16x16x32_bf16 v[110:113], v[126:129], v[186:189], v[110:113]
	v_mfma_f32_16x16x32_bf16 v[110:113], v[122:125], v[182:185], v[110:113]
	v_mfma_f32_16x16x32_bf16 v[94:97], v[122:125], v[190:193], v[94:97]
	v_mfma_f32_16x16x32_bf16 v[94:97], v[126:129], v[200:203], v[94:97]
	v_mfma_f32_16x16x32_bf16 v[90:93], v[142:145], v[200:203], v[90:93]
	v_mfma_f32_16x16x32_bf16 v[90:93], v[138:141], v[190:193], v[90:93]
	v_mfma_f32_16x16x32_bf16 v[86:89], v[146:149], v[190:193], v[86:89]
	v_mfma_f32_16x16x32_bf16 v[86:89], v[150:153], v[200:203], v[86:89]
	v_mfma_f32_16x16x32_bf16 v[82:85], v[158:161], v[200:203], v[82:85]
	v_mfma_f32_16x16x32_bf16 v[82:85], v[154:157], v[190:193], v[82:85]
	v_mfma_f32_16x16x32_bf16 v[66:69], v[154:157], v[204:207], v[66:69]
	v_mfma_f32_16x16x32_bf16 v[66:69], v[158:161], v[208:211], v[66:69]
	v_mfma_f32_16x16x32_bf16 v[70:73], v[150:153], v[208:211], v[70:73]
	v_mfma_f32_16x16x32_bf16 v[70:73], v[146:149], v[204:207], v[70:73]
	v_mfma_f32_16x16x32_bf16 v[74:77], v[138:141], v[204:207], v[74:77]
	v_mfma_f32_16x16x32_bf16 v[74:77], v[142:145], v[208:211], v[74:77]
	v_mfma_f32_16x16x32_bf16 v[78:81], v[126:129], v[208:211], v[78:81]
	v_mfma_f32_16x16x32_bf16 v[78:81], v[122:125], v[204:207], v[78:81]
	s_setprio 0
	s_barrier
	s_add_i32 s12, s23, s42
	v_lshl_add_u64 v[212:213], v[212:213], 0, s[62:63]
	s_mov_b32 m0, s12
	ds_read_b128 v[174:177], v198 offset:49152
	ds_read_b128 v[178:181], v198 offset:50176
	ds_read_b128 v[182:185], v198 offset:51200
	ds_read_b128 v[186:189], v198 offset:52224
	ds_read_b128 v[190:193], v198 offset:53248
	ds_read_b128 v[200:203], v198 offset:54272
	ds_read_b128 v[204:207], v198 offset:55296
	ds_read_b128 v[208:211], v198 offset:56320
	global_load_lds_dwordx4 v[212:213], off
	s_add_i32 m0, s12, 0x2000
	s_add_u32 s12, s50, 0x158080
	v_lshl_add_u64 v[212:213], v[232:233], 0, s[62:63]
	s_addc_u32 s13, s51, 0
	s_add_i32 s23, s24, s42
	global_load_lds_dwordx4 v[212:213], off
	v_lshl_add_u64 v[212:213], s[12:13], 0, v[164:165]
	s_mov_b32 m0, s23
	s_nop 0
	global_load_lds_dwordx4 v[212:213], off
	v_lshl_add_u64 v[212:213], s[12:13], 0, v[168:169]
	s_add_i32 m0, s23, 0x2000
	s_nop 0
	global_load_lds_dwordx4 v[212:213], off
	v_lshl_add_u64 v[212:213], v[234:235], 0, s[62:63]
	s_mov_b32 m0, s1
	s_nop 0
	global_load_lds_dwordx4 v[212:213], off
	v_lshl_add_u64 v[212:213], v[236:237], 0, s[62:63]
	s_mov_b32 m0, s52
	s_nop 0
	global_load_lds_dwordx4 v[212:213], off
	s_waitcnt vmcnt(8)
	s_waitcnt lgkmcnt(0)
	s_barrier
	s_setprio 1
	s_waitcnt lgkmcnt(0)
	v_mfma_f32_16x16x32_bf16 v[62:65], v[122:125], v[174:177], v[62:65]
	v_mfma_f32_16x16x32_bf16 v[62:65], v[126:129], v[178:181], v[62:65]
	v_mfma_f32_16x16x32_bf16 v[58:61], v[142:145], v[178:181], v[58:61]
	v_mfma_f32_16x16x32_bf16 v[58:61], v[138:141], v[174:177], v[58:61]
	v_mfma_f32_16x16x32_bf16 v[54:57], v[146:149], v[174:177], v[54:57]
	v_mfma_f32_16x16x32_bf16 v[54:57], v[150:153], v[178:181], v[54:57]
	v_mfma_f32_16x16x32_bf16 v[50:53], v[158:161], v[178:181], v[50:53]
	v_mfma_f32_16x16x32_bf16 v[50:53], v[154:157], v[174:177], v[50:53]
	v_mfma_f32_16x16x32_bf16 v[34:37], v[154:157], v[182:185], v[34:37]
	v_mfma_f32_16x16x32_bf16 v[34:37], v[158:161], v[186:189], v[34:37]
	v_mfma_f32_16x16x32_bf16 v[38:41], v[150:153], v[186:189], v[38:41]
	v_mfma_f32_16x16x32_bf16 v[38:41], v[146:149], v[182:185], v[38:41]
	v_mfma_f32_16x16x32_bf16 v[42:45], v[138:141], v[182:185], v[42:45]
	v_mfma_f32_16x16x32_bf16 v[42:45], v[142:145], v[186:189], v[42:45]
	v_mfma_f32_16x16x32_bf16 v[46:49], v[126:129], v[186:189], v[46:49]
	v_mfma_f32_16x16x32_bf16 v[46:49], v[122:125], v[182:185], v[46:49]
	v_mfma_f32_16x16x32_bf16 v[30:33], v[122:125], v[190:193], v[30:33]
	v_mfma_f32_16x16x32_bf16 v[30:33], v[126:129], v[200:203], v[30:33]
	v_mfma_f32_16x16x32_bf16 v[26:29], v[142:145], v[200:203], v[26:29]
	v_mfma_f32_16x16x32_bf16 v[26:29], v[138:141], v[190:193], v[26:29]
	v_mfma_f32_16x16x32_bf16 v[22:25], v[146:149], v[190:193], v[22:25]
	v_mfma_f32_16x16x32_bf16 v[22:25], v[150:153], v[200:203], v[22:25]
	v_mfma_f32_16x16x32_bf16 v[18:21], v[158:161], v[200:203], v[18:21]
	v_mfma_f32_16x16x32_bf16 v[18:21], v[154:157], v[190:193], v[18:21]
	v_mfma_f32_16x16x32_bf16 v[2:5], v[154:157], v[204:207], v[2:5]
	v_mfma_f32_16x16x32_bf16 v[2:5], v[158:161], v[208:211], v[2:5]
	v_mfma_f32_16x16x32_bf16 v[6:9], v[150:153], v[208:211], v[6:9]
	v_mfma_f32_16x16x32_bf16 v[6:9], v[146:149], v[204:207], v[6:9]
	v_mfma_f32_16x16x32_bf16 v[10:13], v[138:141], v[204:207], v[10:13]
	v_mfma_f32_16x16x32_bf16 v[10:13], v[142:145], v[208:211], v[10:13]
	v_mfma_f32_16x16x32_bf16 v[14:17], v[126:129], v[208:211], v[14:17]
	v_mfma_f32_16x16x32_bf16 v[14:17], v[122:125], v[204:207], v[14:17]
	s_setprio 0
	s_barrier
	s_add_i32 s22, s22, 2
	s_add_u32 s20, s20, 0x100
	s_addc_u32 s21, s21, 0
	s_cmpk_gt_u32 s22, 0x53
	s_mov_b64 s[12:13], s[10:11]
	s_cbranch_scc0 .LBB0_238
	s_and_b64 vcc, exec, s[2:3]
	s_cbranch_vccz .LBB0_241
	s_barrier

.LBB0_340:
	s_add_u32 s22, s46, 0xfff80080
	s_addc_u32 s23, s47, -1
	s_add_i32 s24, 0, 0x10000
	s_cmp_eq_u32 s21, 28
	s_cselect_b32 s51, s1, s23
	s_cselect_b32 s50, s13, s22
	v_add_u32_e32 v148, s24, v152
	s_cselect_b32 s49, s11, s20
	s_cselect_b32 s48, s18, s19
	s_add_i32 s25, 0, 0x14000
	ds_read_b128 v[144:147], v148
	ds_read_b128 v[156:159], v148 offset:1024
	ds_read_b128 v[160:163], v148 offset:2048
	ds_read_b128 v[164:167], v148 offset:3072
	v_add_u32_e32 v148, s25, v152
	ds_read_b128 v[168:171], v148
	ds_read_b128 v[172:175], v148 offset:1024
	ds_read_b128 v[176:179], v148 offset:2048
	ds_read_b128 v[180:183], v148 offset:3072
	v_lshl_add_u64 v[148:149], s[46:47], 0, v[140:141]
	s_add_i32 m0, s3, 0xc000
	ds_read_b128 v[184:187], v154
	ds_read_b128 v[188:191], v154 offset:1024
	ds_read_b128 v[192:195], v154 offset:2048
	ds_read_b128 v[196:199], v154 offset:3072
	ds_read_b128 v[200:203], v154 offset:4096
	ds_read_b128 v[204:207], v154 offset:5120
	ds_read_b128 v[208:211], v154 offset:6144
	ds_read_b128 v[232:235], v154 offset:7168
	global_load_lds_dwordx4 v[148:149], off
	v_lshl_add_u64 v[148:149], s[46:47], 0, v[142:143]
	s_add_i32 m0, s3, 0xe000
	s_nop 0
	global_load_lds_dwordx4 v[148:149], off
	s_waitcnt vmcnt(8)
	s_waitcnt lgkmcnt(0)
	s_barrier
	s_setprio 1
	s_waitcnt lgkmcnt(0)
	v_mfma_f32_16x16x32_bf16 v[126:129], v[144:147], v[184:187], v[126:129]
	v_mfma_f32_16x16x32_bf16 v[126:129], v[156:159], v[188:191], v[126:129]
	v_mfma_f32_16x16x32_bf16 v[122:125], v[164:167], v[188:191], v[122:125]
	v_mfma_f32_16x16x32_bf16 v[122:125], v[160:163], v[184:187], v[122:125]
	v_mfma_f32_16x16x32_bf16 v[118:121], v[168:171], v[184:187], v[118:121]
	v_mfma_f32_16x16x32_bf16 v[118:121], v[172:175], v[188:191], v[118:121]
	v_mfma_f32_16x16x32_bf16 v[114:117], v[180:183], v[188:191], v[114:117]
	v_mfma_f32_16x16x32_bf16 v[114:117], v[176:179], v[184:187], v[114:117]
	v_mfma_f32_16x16x32_bf16 v[98:101], v[176:179], v[192:195], v[98:101]
	v_mfma_f32_16x16x32_bf16 v[98:101], v[180:183], v[196:199], v[98:101]
	v_mfma_f32_16x16x32_bf16 v[102:105], v[172:175], v[196:199], v[102:105]
	v_mfma_f32_16x16x32_bf16 v[102:105], v[168:171], v[192:195], v[102:105]
	v_mfma_f32_16x16x32_bf16 v[106:109], v[160:163], v[192:195], v[106:109]
	v_mfma_f32_16x16x32_bf16 v[106:109], v[164:167], v[196:199], v[106:109]
	v_mfma_f32_16x16x32_bf16 v[110:113], v[156:159], v[196:199], v[110:113]
	v_mfma_f32_16x16x32_bf16 v[110:113], v[144:147], v[192:195], v[110:113]
	v_mfma_f32_16x16x32_bf16 v[94:97], v[144:147], v[200:203], v[94:97]
	v_mfma_f32_16x16x32_bf16 v[94:97], v[156:159], v[204:207], v[94:97]
	v_mfma_f32_16x16x32_bf16 v[90:93], v[164:167], v[204:207], v[90:93]
	v_mfma_f32_16x16x32_bf16 v[90:93], v[160:163], v[200:203], v[90:93]
	v_mfma_f32_16x16x32_bf16 v[86:89], v[168:171], v[200:203], v[86:89]
	v_mfma_f32_16x16x32_bf16 v[86:89], v[172:175], v[204:207], v[86:89]
	v_mfma_f32_16x16x32_bf16 v[82:85], v[180:183], v[204:207], v[82:85]
	v_mfma_f32_16x16x32_bf16 v[82:85], v[176:179], v[200:203], v[82:85]
	v_mfma_f32_16x16x32_bf16 v[66:69], v[176:179], v[208:211], v[66:69]
	v_mfma_f32_16x16x32_bf16 v[66:69], v[180:183], v[232:235], v[66:69]
	v_mfma_f32_16x16x32_bf16 v[70:73], v[172:175], v[232:235], v[70:73]
	v_mfma_f32_16x16x32_bf16 v[70:73], v[168:171], v[208:211], v[70:73]
	v_mfma_f32_16x16x32_bf16 v[74:77], v[160:163], v[208:211], v[74:77]
	v_mfma_f32_16x16x32_bf16 v[74:77], v[164:167], v[232:235], v[74:77]
	v_mfma_f32_16x16x32_bf16 v[78:81], v[156:159], v[232:235], v[78:81]
	v_mfma_f32_16x16x32_bf16 v[78:81], v[144:147], v[208:211], v[78:81]
	s_setprio 0
	s_barrier
	s_add_i32 s22, s24, s16
	v_lshl_add_u64 v[148:149], s[48:49], 0, v[134:135]
	s_mov_b32 m0, s22
	ds_read_b128 v[184:187], v154 offset:16384
	ds_read_b128 v[188:191], v154 offset:17408
	ds_read_b128 v[192:195], v154 offset:18432
	ds_read_b128 v[196:199], v154 offset:19456
	ds_read_b128 v[200:203], v154 offset:20480
	ds_read_b128 v[204:207], v154 offset:21504
	ds_read_b128 v[208:211], v154 offset:22528
	ds_read_b128 v[232:235], v154 offset:23552
	global_load_lds_dwordx4 v[148:149], off
	s_add_i32 m0, s22, 0x2000
	s_add_u32 s22, s48, 0x80000
	v_lshl_add_u64 v[212:213], s[48:49], 0, v[130:131]
	s_addc_u32 s23, s49, 0
	s_add_i32 s24, s25, s16
	global_load_lds_dwordx4 v[212:213], off
	v_lshl_add_u64 v[236:237], s[22:23], 0, v[134:135]
	s_mov_b32 m0, s24
	v_lshl_add_u64 v[238:239], s[50:51], 0, v[132:133]
	global_load_lds_dwordx4 v[236:237], off
	v_lshl_add_u64 v[236:237], s[22:23], 0, v[130:131]
	s_add_i32 m0, s24, 0x2000
	s_nop 0
	global_load_lds_dwordx4 v[236:237], off
	v_lshl_add_u64 v[236:237], s[50:51], 0, v[136:137]
	s_mov_b32 m0, s3
	s_nop 0
	global_load_lds_dwordx4 v[236:237], off
	s_mov_b32 m0, s55
	s_nop 0
	global_load_lds_dwordx4 v[238:239], off
	s_waitcnt vmcnt(8)
	s_waitcnt lgkmcnt(0)
	s_barrier
	s_setprio 1
	s_waitcnt lgkmcnt(0)
	v_mfma_f32_16x16x32_bf16 v[62:65], v[144:147], v[184:187], v[62:65]
	v_mfma_f32_16x16x32_bf16 v[62:65], v[156:159], v[188:191], v[62:65]
	v_mfma_f32_16x16x32_bf16 v[58:61], v[164:167], v[188:191], v[58:61]
	v_mfma_f32_16x16x32_bf16 v[58:61], v[160:163], v[184:187], v[58:61]
	v_mfma_f32_16x16x32_bf16 v[54:57], v[168:171], v[184:187], v[54:57]
	v_mfma_f32_16x16x32_bf16 v[54:57], v[172:175], v[188:191], v[54:57]
	v_mfma_f32_16x16x32_bf16 v[50:53], v[180:183], v[188:191], v[50:53]
	v_mfma_f32_16x16x32_bf16 v[50:53], v[176:179], v[184:187], v[50:53]
	v_mfma_f32_16x16x32_bf16 v[34:37], v[176:179], v[192:195], v[34:37]
	v_mfma_f32_16x16x32_bf16 v[34:37], v[180:183], v[196:199], v[34:37]
	v_mfma_f32_16x16x32_bf16 v[38:41], v[172:175], v[196:199], v[38:41]
	v_mfma_f32_16x16x32_bf16 v[38:41], v[168:171], v[192:195], v[38:41]
	v_mfma_f32_16x16x32_bf16 v[42:45], v[160:163], v[192:195], v[42:45]
	v_mfma_f32_16x16x32_bf16 v[42:45], v[164:167], v[196:199], v[42:45]
	v_mfma_f32_16x16x32_bf16 v[46:49], v[156:159], v[196:199], v[46:49]
	v_mfma_f32_16x16x32_bf16 v[46:49], v[144:147], v[192:195], v[46:49]
	v_mfma_f32_16x16x32_bf16 v[30:33], v[144:147], v[200:203], v[30:33]
	v_mfma_f32_16x16x32_bf16 v[30:33], v[156:159], v[204:207], v[30:33]
	v_mfma_f32_16x16x32_bf16 v[26:29], v[164:167], v[204:207], v[26:29]
	v_mfma_f32_16x16x32_bf16 v[26:29], v[160:163], v[200:203], v[26:29]
	v_mfma_f32_16x16x32_bf16 v[22:25], v[168:171], v[200:203], v[22:25]
	v_mfma_f32_16x16x32_bf16 v[22:25], v[172:175], v[204:207], v[22:25]
	v_mfma_f32_16x16x32_bf16 v[18:21], v[180:183], v[204:207], v[18:21]
	v_mfma_f32_16x16x32_bf16 v[18:21], v[176:179], v[200:203], v[18:21]
	v_mfma_f32_16x16x32_bf16 v[2:5], v[176:179], v[208:211], v[2:5]
	v_mfma_f32_16x16x32_bf16 v[2:5], v[180:183], v[232:235], v[2:5]
	v_mfma_f32_16x16x32_bf16 v[6:9], v[172:175], v[232:235], v[6:9]
	v_mfma_f32_16x16x32_bf16 v[6:9], v[168:171], v[208:211], v[6:9]
	v_mfma_f32_16x16x32_bf16 v[10:13], v[160:163], v[208:211], v[10:13]
	v_mfma_f32_16x16x32_bf16 v[10:13], v[164:167], v[232:235], v[10:13]
	v_mfma_f32_16x16x32_bf16 v[14:17], v[156:159], v[232:235], v[14:17]
	v_mfma_f32_16x16x32_bf16 v[14:17], v[144:147], v[208:211], v[14:17]
	s_setprio 0
	s_barrier
	s_add_i32 s24, 0, 0x18000
	v_add_u32_e32 v155, s24, v152
	s_add_i32 s25, 0, 0x1c000
	ds_read_b128 v[144:147], v155
	ds_read_b128 v[156:159], v155 offset:1024
	ds_read_b128 v[160:163], v155 offset:2048
	ds_read_b128 v[164:167], v155 offset:3072
	v_add_u32_e32 v155, s25, v152
	ds_read_b128 v[168:171], v155
	ds_read_b128 v[172:175], v155 offset:1024
	ds_read_b128 v[176:179], v155 offset:2048
	ds_read_b128 v[180:183], v155 offset:3072
	s_add_u32 s22, s50, 0x80000
	s_addc_u32 s23, s51, 0
	s_mov_b32 m0, s57
	v_lshl_add_u64 v[240:241], s[22:23], 0, v[136:137]
	ds_read_b128 v[184:187], v154 offset:32768
	ds_read_b128 v[188:191], v154 offset:33792
	ds_read_b128 v[192:195], v154 offset:34816
	ds_read_b128 v[196:199], v154 offset:35840
	ds_read_b128 v[200:203], v154 offset:36864
	ds_read_b128 v[204:207], v154 offset:37888
	ds_read_b128 v[208:211], v154 offset:38912
	ds_read_b128 v[232:235], v154 offset:39936
	global_load_lds_dwordx4 v[240:241], off
	v_lshl_add_u64 v[240:241], s[22:23], 0, v[132:133]
	s_mov_b32 m0, s68
	s_nop 0
	global_load_lds_dwordx4 v[240:241], off
	s_waitcnt vmcnt(8)
	s_waitcnt lgkmcnt(0)
	s_barrier
	s_setprio 1
	s_waitcnt lgkmcnt(0)
	v_mfma_f32_16x16x32_bf16 v[126:129], v[144:147], v[184:187], v[126:129]
	v_mfma_f32_16x16x32_bf16 v[126:129], v[156:159], v[188:191], v[126:129]
	v_mfma_f32_16x16x32_bf16 v[122:125], v[164:167], v[188:191], v[122:125]
	v_mfma_f32_16x16x32_bf16 v[122:125], v[160:163], v[184:187], v[122:125]
	v_mfma_f32_16x16x32_bf16 v[118:121], v[168:171], v[184:187], v[118:121]
	v_mfma_f32_16x16x32_bf16 v[118:121], v[172:175], v[188:191], v[118:121]
	v_mfma_f32_16x16x32_bf16 v[114:117], v[180:183], v[188:191], v[114:117]
	v_mfma_f32_16x16x32_bf16 v[114:117], v[176:179], v[184:187], v[114:117]
	v_mfma_f32_16x16x32_bf16 v[98:101], v[176:179], v[192:195], v[98:101]
	v_mfma_f32_16x16x32_bf16 v[98:101], v[180:183], v[196:199], v[98:101]
	v_mfma_f32_16x16x32_bf16 v[102:105], v[172:175], v[196:199], v[102:105]
	v_mfma_f32_16x16x32_bf16 v[102:105], v[168:171], v[192:195], v[102:105]
	v_mfma_f32_16x16x32_bf16 v[106:109], v[160:163], v[192:195], v[106:109]
	v_mfma_f32_16x16x32_bf16 v[106:109], v[164:167], v[196:199], v[106:109]
	v_mfma_f32_16x16x32_bf16 v[110:113], v[156:159], v[196:199], v[110:113]
	v_mfma_f32_16x16x32_bf16 v[110:113], v[144:147], v[192:195], v[110:113]
	v_mfma_f32_16x16x32_bf16 v[94:97], v[144:147], v[200:203], v[94:97]
	v_mfma_f32_16x16x32_bf16 v[94:97], v[156:159], v[204:207], v[94:97]
	v_mfma_f32_16x16x32_bf16 v[90:93], v[164:167], v[204:207], v[90:93]
	v_mfma_f32_16x16x32_bf16 v[90:93], v[160:163], v[200:203], v[90:93]
	v_mfma_f32_16x16x32_bf16 v[86:89], v[168:171], v[200:203], v[86:89]
	v_mfma_f32_16x16x32_bf16 v[86:89], v[172:175], v[204:207], v[86:89]
	v_mfma_f32_16x16x32_bf16 v[82:85], v[180:183], v[204:207], v[82:85]
	v_mfma_f32_16x16x32_bf16 v[82:85], v[176:179], v[200:203], v[82:85]
	v_mfma_f32_16x16x32_bf16 v[66:69], v[176:179], v[208:211], v[66:69]
	v_mfma_f32_16x16x32_bf16 v[66:69], v[180:183], v[232:235], v[66:69]
	v_mfma_f32_16x16x32_bf16 v[70:73], v[172:175], v[232:235], v[70:73]
	v_mfma_f32_16x16x32_bf16 v[70:73], v[168:171], v[208:211], v[70:73]
	v_mfma_f32_16x16x32_bf16 v[74:77], v[160:163], v[208:211], v[74:77]
	v_mfma_f32_16x16x32_bf16 v[74:77], v[164:167], v[232:235], v[74:77]
	v_mfma_f32_16x16x32_bf16 v[78:81], v[156:159], v[232:235], v[78:81]
	v_mfma_f32_16x16x32_bf16 v[78:81], v[144:147], v[208:211], v[78:81]
	s_setprio 0
	s_barrier
	s_add_i32 s22, s24, s16
	v_lshl_add_u64 v[148:149], v[148:149], 0, s[62:63]
	s_mov_b32 m0, s22
	ds_read_b128 v[184:187], v154 offset:49152
	ds_read_b128 v[188:191], v154 offset:50176
	ds_read_b128 v[192:195], v154 offset:51200
	ds_read_b128 v[196:199], v154 offset:52224
	ds_read_b128 v[200:203], v154 offset:53248
	ds_read_b128 v[204:207], v154 offset:54272
	ds_read_b128 v[208:211], v154 offset:55296
	ds_read_b128 v[232:235], v154 offset:56320
	global_load_lds_dwordx4 v[148:149], off
	s_add_i32 m0, s22, 0x2000
	s_add_u32 s22, s48, 0x80080
	v_lshl_add_u64 v[148:149], v[212:213], 0, s[62:63]
	s_addc_u32 s23, s49, 0
	s_add_i32 s24, s25, s16
	global_load_lds_dwordx4 v[148:149], off
	v_lshl_add_u64 v[148:149], s[22:23], 0, v[134:135]
	s_mov_b32 m0, s24
	s_nop 0
	global_load_lds_dwordx4 v[148:149], off
	v_lshl_add_u64 v[148:149], s[22:23], 0, v[130:131]
	s_add_i32 m0, s24, 0x2000
	s_nop 0
	global_load_lds_dwordx4 v[148:149], off
	v_lshl_add_u64 v[148:149], v[236:237], 0, s[62:63]
	s_mov_b32 m0, s69
	s_nop 0
	global_load_lds_dwordx4 v[148:149], off
	v_lshl_add_u64 v[148:149], v[238:239], 0, s[62:63]
	s_mov_b32 m0, s70
	s_nop 0
	global_load_lds_dwordx4 v[148:149], off
	s_waitcnt vmcnt(8)
	s_waitcnt lgkmcnt(0)
	s_barrier
	s_setprio 1
	s_waitcnt lgkmcnt(0)
	v_mfma_f32_16x16x32_bf16 v[62:65], v[144:147], v[184:187], v[62:65]
	v_mfma_f32_16x16x32_bf16 v[62:65], v[156:159], v[188:191], v[62:65]
	v_mfma_f32_16x16x32_bf16 v[58:61], v[164:167], v[188:191], v[58:61]
	v_mfma_f32_16x16x32_bf16 v[58:61], v[160:163], v[184:187], v[58:61]
	v_mfma_f32_16x16x32_bf16 v[54:57], v[168:171], v[184:187], v[54:57]
	v_mfma_f32_16x16x32_bf16 v[54:57], v[172:175], v[188:191], v[54:57]
	v_mfma_f32_16x16x32_bf16 v[50:53], v[180:183], v[188:191], v[50:53]
	v_mfma_f32_16x16x32_bf16 v[50:53], v[176:179], v[184:187], v[50:53]
	v_mfma_f32_16x16x32_bf16 v[34:37], v[176:179], v[192:195], v[34:37]
	v_mfma_f32_16x16x32_bf16 v[34:37], v[180:183], v[196:199], v[34:37]
	v_mfma_f32_16x16x32_bf16 v[38:41], v[172:175], v[196:199], v[38:41]
	v_mfma_f32_16x16x32_bf16 v[38:41], v[168:171], v[192:195], v[38:41]
	v_mfma_f32_16x16x32_bf16 v[42:45], v[160:163], v[192:195], v[42:45]
	v_mfma_f32_16x16x32_bf16 v[42:45], v[164:167], v[196:199], v[42:45]
	v_mfma_f32_16x16x32_bf16 v[46:49], v[156:159], v[196:199], v[46:49]
	v_mfma_f32_16x16x32_bf16 v[46:49], v[144:147], v[192:195], v[46:49]
	v_mfma_f32_16x16x32_bf16 v[30:33], v[144:147], v[200:203], v[30:33]
	v_mfma_f32_16x16x32_bf16 v[30:33], v[156:159], v[204:207], v[30:33]
	v_mfma_f32_16x16x32_bf16 v[26:29], v[164:167], v[204:207], v[26:29]
	v_mfma_f32_16x16x32_bf16 v[26:29], v[160:163], v[200:203], v[26:29]
	v_mfma_f32_16x16x32_bf16 v[22:25], v[168:171], v[200:203], v[22:25]
	v_mfma_f32_16x16x32_bf16 v[22:25], v[172:175], v[204:207], v[22:25]
	v_mfma_f32_16x16x32_bf16 v[18:21], v[180:183], v[204:207], v[18:21]
	v_mfma_f32_16x16x32_bf16 v[18:21], v[176:179], v[200:203], v[18:21]
	v_mfma_f32_16x16x32_bf16 v[2:5], v[176:179], v[208:211], v[2:5]
	v_mfma_f32_16x16x32_bf16 v[2:5], v[180:183], v[232:235], v[2:5]
	v_mfma_f32_16x16x32_bf16 v[6:9], v[172:175], v[232:235], v[6:9]
	v_mfma_f32_16x16x32_bf16 v[6:9], v[168:171], v[208:211], v[6:9]
	v_mfma_f32_16x16x32_bf16 v[10:13], v[160:163], v[208:211], v[10:13]
	v_mfma_f32_16x16x32_bf16 v[10:13], v[164:167], v[232:235], v[10:13]
	v_mfma_f32_16x16x32_bf16 v[14:17], v[156:159], v[232:235], v[14:17]
	v_mfma_f32_16x16x32_bf16 v[14:17], v[144:147], v[208:211], v[14:17]
	s_setprio 0
	s_barrier
	s_add_i32 s21, s21, 2
	s_add_u32 s46, s46, 0x100
	s_addc_u32 s47, s47, 0
	s_add_u32 s19, s19, 0x100
	s_addc_u32 s20, s20, 0
	s_cmp_gt_u32 s21, 29
	s_cbranch_scc0 .LBB0_340
	s_and_b64 vcc, exec, s[8:9]
	s_cbranch_vccz .LBB0_343
	s_barrier
